# P10: per-token bitonic sort of the 128 selected expert slots by row so all waves sweep the fp4 expert tables in ascending order (better L2 reuse); plus P4 rewrite
# speedup vs baseline: 1.0365x; 1.0077x over previous
; __device__ __forceinline__ float bf_lo(unsigned u) { return __uint_as_float(u << 16); }
; __device__ __forceinline__ float bf_hi(unsigned u) { return __uint_as_float(u & 0xffff0000u); }
; __global__ void __launch_bounds__(NT, 2) mk_fwd(Args args) {
;     ...
;     if (IN(10)) {
;         const float* fg = args.in[28];
;         for (int tok = gw; tok < MTOK; tok += NGW) {
;             const int b = tok >> 11;
;             f32x2 hf2[16];
; #pragma unroll
;             for (int j = 0; j < 4; ++j) { const u32x4 a = *(const u32x4*)(HB + (size_t)tok * DM + lane * 32 + j * 8);
; #pragma unroll
;                 for (int q = 0; q < 4; ++q) hf2[j * 4 + q] = (f32x2){bf_lo(a[q]), bf_hi(a[q])}; }
;             const int e0 = EIDX[(size_t)tok * 128 + lane], e1 = EIDX[(size_t)tok * 128 + 64 + lane];
;             const float g0 = GATE[(size_t)tok * 128 + lane], g1 = GATE[(size_t)tok * 128 + 64 + lane];
;             const bool hi32 = (lane & 32) != 0, hi16 = (lane & 16) != 0; const int l3 = (lane & 3) << 4;
.LBB0_883:
	s_cmp_lt_i32 s94, 11
	s_cselect_b64 s[2:3], -1, 0
	s_and_b64 s[0:1], s[2:3], s[0:1]
	s_and_b64 s[0:1], s[0:1], s[86:87]
	s_andn2_b64 vcc, exec, s[0:1]
	s_cbranch_vccnz .LBB0_913
	s_waitcnt vmcnt(0)
	v_mbcnt_hi_u32_b32 v3, -1, v169
	v_and_b32_e32 v5, 64, v3
	v_xor_b32_e32 v4, 32, v3
	v_add_u32_e32 v6, 64, v5
	v_cmp_lt_i32_e32 vcc, v4, v6
	v_mov_b32_e32 v137, 0
	v_and_b32_e32 v0, 32, v168
	v_cndmask_b32_e32 v4, v3, v4, vcc
	v_cmp_eq_u32_e64 s[0:1], 0, v0
	v_and_b32_e32 v0, 16, v168
	v_mov_b32_e32 v131, v137
	v_lshlrev_b32_e32 v129, 2, v4
	v_xor_b32_e32 v4, 16, v3
	v_cmp_eq_u32_e64 s[2:3], 0, v0
	v_lshlrev_b32_e32 v2, 4, v168
	v_lshl_add_u64 v[0:1], s[92:93], 0, v[130:131]
	s_mov_b64 s[4:5], 0x2a00000
	v_cmp_lt_i32_e32 vcc, v4, v6
	s_add_u32 s6, s92, 0x6a00000
	v_lshl_add_u64 v[96:97], s[80:81], 0, v[136:137]
	v_lshl_add_u64 v[98:99], v[0:1], 0, s[4:5]
	v_cndmask_b32_e32 v3, v3, v4, vcc
	v_and_or_b32 v2, v2, 48, v5
	s_mov_b64 s[4:5], 0x4a00000
	v_lshlrev_b32_e32 v136, 7, v128
	v_and_b32_e32 v148, 60, v128
	s_addc_u32 s7, s93, 0
	v_lshlrev_b32_e32 v146, 2, v3
	v_lshlrev_b32_e32 v147, 2, v2
	v_lshl_add_u64 v[100:101], v[0:1], 0, s[4:5]
	v_lshl_add_u64 v[102:103], s[90:91], 0, v[136:137]
	v_lshl_add_u64 v[104:105], s[88:89], 0, v[136:137]
	v_add_u32_e32 v149, -12, v148
	v_add_u32_e32 v150, -8, v148
	v_add_u32_e32 v151, -4, v148
	s_mov_b32 s11, 0x378e98ab
	s_mov_b32 s13, 0x3b7cd369
	s_mov_b32 s15, 0xbcc618b2
	s_mov_b32 s17, 0x3dda74e4
	s_mov_b32 s19, 0x3f228afd
	s_mov_b32 s21, 0x3e03c728
	s_mov_b32 s23, 0xbfb8aa3b
	s_mov_b32 s25, 0x42ce8ed0
	s_mov_b32 s26, 0xc2b17218
	v_mov_b32_e32 v152, 0x3ba10414
	s_brev_b32 s27, -2
	v_lshlrev_b32_e32 v136, 2, v138
	s_mov_b64 s[8:9], 0xa000
	s_mov_b32 s28, 0xa000
	v_mov_b32_e32 v153, 0x358637bd
	s_mov_b32 s29, 0x800000
	v_mov_b32_e32 v154, 0xb9c68948
	v_mov_b32_e32 v155, 0x7f800000
	s_mov_b32 s50, 0x55555555
	s_mov_b32 s51, 0x55555555
	s_mov_b32 s52, 0x33333333
	s_mov_b32 s53, 0x33333333
	s_mov_b32 s54, 0xf0f0f0f
	s_mov_b32 s55, 0xf0f0f0f
	s_mov_b32 s56, 0xff00ff
	s_mov_b32 s57, 0xff00ff
	s_mov_b32 s58, 0xffff
	s_mov_b32 s59, 0xffff
	s_mov_b32 s60, -1
	s_mov_b32 s61, 0
	s_branch .LBB0_886

; __device__ __forceinline__ float bf_lo(unsigned u) { return __uint_as_float(u << 16); }
; __device__ __forceinline__ float bf_hi(unsigned u) { return __uint_as_float(u & 0xffff0000u); }
; __global__ void __launch_bounds__(NT, 2) mk_fwd(Args args) {
;     ...
;             for (int j = 0; j < 4; ++j) { const u32x4 a = *(const u32x4*)(HB + (size_t)tok * DM + lane * 32 + j * 8);
; #pragma unroll
;                 for (int q = 0; q < 4; ++q) hf2[j * 4 + q] = (f32x2){bf_lo(a[q]), bf_hi(a[q])}; }
;             const int e0 = EIDX[(size_t)tok * 128 + lane], e1 = EIDX[(size_t)tok * 128 + 64 + lane];
;             const float g0 = GATE[(size_t)tok * 128 + lane], g1 = GATE[(size_t)tok * 128 + 64 + lane];
.LBB0_886:
	s_ashr_i32 s71, s70, 31
	s_lshl_b64 s[4:5], s[70:71], 9
	v_lshl_or_b32 v0, v128, 2, s4
	v_mov_b32_e32 v1, s5
	v_lshl_add_u64 v[2:3], s[46:47], 0, v[0:1]
	global_load_dword v108, v[2:3], off
	s_lshl_b64 s[4:5], s[70:71], 12
	v_lshl_add_u64 v[2:3], v[96:97], 0, s[4:5]
	global_load_dwordx4 v[32:35], v[2:3], off offset:48
	global_load_dwordx4 v[36:39], v[2:3], off offset:32
	global_load_dwordx4 v[40:43], v[2:3], off offset:16
	global_load_dwordx4 v[44:47], v[2:3], off
	v_or_b32_e32 v2, 0x100, v0
	v_mov_b32_e32 v3, v1
	v_lshl_add_u64 v[0:1], s[48:49], 0, v[0:1]
	v_lshl_add_u64 v[4:5], s[46:47], 0, v[2:3]
	v_lshl_add_u64 v[2:3], s[48:49], 0, v[2:3]
	global_load_dword v106, v[4:5], off
	global_load_dword v110, v[0:1], off
	global_load_dword v156, v[2:3], off
	s_waitcnt vmcnt(0)
	v_lshl_or_b32 v170, v108, 7, v128
	v_lshlrev_b32_e32 v171, 7, v106
	v_or_b32_e32 v174, 64, v128
	v_or_b32_e32 v171, v171, v174
	s_nop 0
	s_xnor_b64 s[62:63], s[50:51], s[52:53]
	s_nop 1
	v_min_u32_dpp v172, v170, v170 quad_perm:[1,0,3,2] row_mask:0xf bank_mask:0xf
	v_max_u32_dpp v173, v170, v170 quad_perm:[1,0,3,2] row_mask:0xf bank_mask:0xf
	v_min_u32_dpp v175, v171, v171 quad_perm:[1,0,3,2] row_mask:0xf bank_mask:0xf
	v_max_u32_dpp v176, v171, v171 quad_perm:[1,0,3,2] row_mask:0xf bank_mask:0xf
	v_cndmask_b32_e64 v170, v173, v172, s[62:63]
	v_cndmask_b32_e64 v171, v176, v175, s[62:63]
	s_xnor_b64 s[62:63], s[52:53], s[54:55]
	s_nop 1
	v_min_u32_dpp v172, v170, v170 quad_perm:[2,3,0,1] row_mask:0xf bank_mask:0xf
	v_max_u32_dpp v173, v170, v170 quad_perm:[2,3,0,1] row_mask:0xf bank_mask:0xf
	v_min_u32_dpp v175, v171, v171 quad_perm:[2,3,0,1] row_mask:0xf bank_mask:0xf
	v_max_u32_dpp v176, v171, v171 quad_perm:[2,3,0,1] row_mask:0xf bank_mask:0xf
	v_cndmask_b32_e64 v170, v173, v172, s[62:63]
	v_cndmask_b32_e64 v171, v176, v175, s[62:63]
	s_xnor_b64 s[62:63], s[50:51], s[54:55]
	s_nop 1
	v_min_u32_dpp v172, v170, v170 quad_perm:[1,0,3,2] row_mask:0xf bank_mask:0xf
	v_max_u32_dpp v173, v170, v170 quad_perm:[1,0,3,2] row_mask:0xf bank_mask:0xf
	v_min_u32_dpp v175, v171, v171 quad_perm:[1,0,3,2] row_mask:0xf bank_mask:0xf
	v_max_u32_dpp v176, v171, v171 quad_perm:[1,0,3,2] row_mask:0xf bank_mask:0xf
	v_cndmask_b32_e64 v170, v173, v172, s[62:63]
	v_cndmask_b32_e64 v171, v176, v175, s[62:63]
	s_xnor_b64 s[62:63], s[54:55], s[56:57]
	s_nop 1
	v_mov_b32_dpp v174, v170 row_half_mirror row_mask:0xf bank_mask:0xf
	v_mov_b32_dpp v177, v171 row_half_mirror row_mask:0xf bank_mask:0xf
	s_nop 0
	v_min_u32_dpp v172, v174, v170 quad_perm:[3,2,1,0] row_mask:0xf bank_mask:0xf
	v_max_u32_dpp v173, v174, v170 quad_perm:[3,2,1,0] row_mask:0xf bank_mask:0xf
	v_min_u32_dpp v175, v177, v171 quad_perm:[3,2,1,0] row_mask:0xf bank_mask:0xf
	v_max_u32_dpp v176, v177, v171 quad_perm:[3,2,1,0] row_mask:0xf bank_mask:0xf
	v_cndmask_b32_e64 v170, v173, v172, s[62:63]
	v_cndmask_b32_e64 v171, v176, v175, s[62:63]
	s_xnor_b64 s[62:63], s[52:53], s[56:57]
	s_nop 1
	v_min_u32_dpp v172, v170, v170 quad_perm:[2,3,0,1] row_mask:0xf bank_mask:0xf
	v_max_u32_dpp v173, v170, v170 quad_perm:[2,3,0,1] row_mask:0xf bank_mask:0xf
	v_min_u32_dpp v175, v171, v171 quad_perm:[2,3,0,1] row_mask:0xf bank_mask:0xf
	v_max_u32_dpp v176, v171, v171 quad_perm:[2,3,0,1] row_mask:0xf bank_mask:0xf
	v_cndmask_b32_e64 v170, v173, v172, s[62:63]
	v_cndmask_b32_e64 v171, v176, v175, s[62:63]
	s_xnor_b64 s[62:63], s[50:51], s[56:57]
	s_nop 1
	v_min_u32_dpp v172, v170, v170 quad_perm:[1,0,3,2] row_mask:0xf bank_mask:0xf
	v_max_u32_dpp v173, v170, v170 quad_perm:[1,0,3,2] row_mask:0xf bank_mask:0xf
	v_min_u32_dpp v175, v171, v171 quad_perm:[1,0,3,2] row_mask:0xf bank_mask:0xf
	v_max_u32_dpp v176, v171, v171 quad_perm:[1,0,3,2] row_mask:0xf bank_mask:0xf
	v_cndmask_b32_e64 v170, v173, v172, s[62:63]
	v_cndmask_b32_e64 v171, v176, v175, s[62:63]
	s_xnor_b64 s[62:63], s[56:57], s[58:59]
	s_nop 1
	v_min_u32_dpp v172, v170, v170 row_ror:8 row_mask:0xf bank_mask:0xf
	v_max_u32_dpp v173, v170, v170 row_ror:8 row_mask:0xf bank_mask:0xf
	v_min_u32_dpp v175, v171, v171 row_ror:8 row_mask:0xf bank_mask:0xf
	v_max_u32_dpp v176, v171, v171 row_ror:8 row_mask:0xf bank_mask:0xf
	v_cndmask_b32_e64 v170, v173, v172, s[62:63]
	v_cndmask_b32_e64 v171, v176, v175, s[62:63]
	s_xnor_b64 s[62:63], s[54:55], s[58:59]
	s_nop 1
	v_mov_b32_dpp v174, v170 row_half_mirror row_mask:0xf bank_mask:0xf
	v_mov_b32_dpp v177, v171 row_half_mirror row_mask:0xf bank_mask:0xf
	s_nop 0
	v_min_u32_dpp v172, v174, v170 quad_perm:[3,2,1,0] row_mask:0xf bank_mask:0xf
	v_max_u32_dpp v173, v174, v170 quad_perm:[3,2,1,0] row_mask:0xf bank_mask:0xf
	v_min_u32_dpp v175, v177, v171 quad_perm:[3,2,1,0] row_mask:0xf bank_mask:0xf
	v_max_u32_dpp v176, v177, v171 quad_perm:[3,2,1,0] row_mask:0xf bank_mask:0xf
	v_cndmask_b32_e64 v170, v173, v172, s[62:63]
	v_cndmask_b32_e64 v171, v176, v175, s[62:63]
	s_xnor_b64 s[62:63], s[52:53], s[58:59]
	s_nop 1
	v_min_u32_dpp v172, v170, v170 quad_perm:[2,3,0,1] row_mask:0xf bank_mask:0xf
	v_max_u32_dpp v173, v170, v170 quad_perm:[2,3,0,1] row_mask:0xf bank_mask:0xf
	v_min_u32_dpp v175, v171, v171 quad_perm:[2,3,0,1] row_mask:0xf bank_mask:0xf
	v_max_u32_dpp v176, v171, v171 quad_perm:[2,3,0,1] row_mask:0xf bank_mask:0xf
	v_cndmask_b32_e64 v170, v173, v172, s[62:63]
	v_cndmask_b32_e64 v171, v176, v175, s[62:63]
	s_xnor_b64 s[62:63], s[50:51], s[58:59]
	s_nop 1
	v_min_u32_dpp v172, v170, v170 quad_perm:[1,0,3,2] row_mask:0xf bank_mask:0xf
	v_max_u32_dpp v173, v170, v170 quad_perm:[1,0,3,2] row_mask:0xf bank_mask:0xf
	v_min_u32_dpp v175, v171, v171 quad_perm:[1,0,3,2] row_mask:0xf bank_mask:0xf
	v_max_u32_dpp v176, v171, v171 quad_perm:[1,0,3,2] row_mask:0xf bank_mask:0xf
	v_cndmask_b32_e64 v170, v173, v172, s[62:63]
	v_cndmask_b32_e64 v171, v176, v175, s[62:63]
	s_xnor_b64 s[62:63], s[58:59], s[60:61]
	ds_bpermute_b32 v174, v146, v170
	ds_bpermute_b32 v177, v146, v171
	s_waitcnt lgkmcnt(1)
; __global__ void __launch_bounds__(NT, 2) mk_fwd(Args args) {
;     ...
;             const int e0 = EIDX[(size_t)tok * 128 + lane], e1 = EIDX[(size_t)tok * 128 + 64 + lane];
;             const float g0 = GATE[(size_t)tok * 128 + lane], g1 = GATE[(size_t)tok * 128 + 64 + lane];
;             const bool hi32 = (lane & 32) != 0, hi16 = (lane & 16) != 0; const int l3 = (lane & 3) << 4;
	v_min_u32_e32 v172, v174, v170
	v_max_u32_e32 v173, v174, v170
	s_waitcnt lgkmcnt(0)
	v_min_u32_e32 v175, v177, v171
	v_max_u32_e32 v176, v177, v171
	v_cndmask_b32_e64 v170, v173, v172, s[62:63]
	v_cndmask_b32_e64 v171, v176, v175, s[62:63]
	s_xnor_b64 s[62:63], s[56:57], s[60:61]
	s_nop 1
	v_min_u32_dpp v172, v170, v170 row_ror:8 row_mask:0xf bank_mask:0xf
	v_max_u32_dpp v173, v170, v170 row_ror:8 row_mask:0xf bank_mask:0xf
	v_min_u32_dpp v175, v171, v171 row_ror:8 row_mask:0xf bank_mask:0xf
	v_max_u32_dpp v176, v171, v171 row_ror:8 row_mask:0xf bank_mask:0xf
	v_cndmask_b32_e64 v170, v173, v172, s[62:63]
	v_cndmask_b32_e64 v171, v176, v175, s[62:63]
	s_xnor_b64 s[62:63], s[54:55], s[60:61]
	s_nop 1
	v_mov_b32_dpp v174, v170 row_half_mirror row_mask:0xf bank_mask:0xf
	v_mov_b32_dpp v177, v171 row_half_mirror row_mask:0xf bank_mask:0xf
	s_nop 0
	v_min_u32_dpp v172, v174, v170 quad_perm:[3,2,1,0] row_mask:0xf bank_mask:0xf
	v_max_u32_dpp v173, v174, v170 quad_perm:[3,2,1,0] row_mask:0xf bank_mask:0xf
	v_min_u32_dpp v175, v177, v171 quad_perm:[3,2,1,0] row_mask:0xf bank_mask:0xf
	v_max_u32_dpp v176, v177, v171 quad_perm:[3,2,1,0] row_mask:0xf bank_mask:0xf
	v_cndmask_b32_e64 v170, v173, v172, s[62:63]
	v_cndmask_b32_e64 v171, v176, v175, s[62:63]
	s_xnor_b64 s[62:63], s[52:53], s[60:61]
	s_nop 1
	v_min_u32_dpp v172, v170, v170 quad_perm:[2,3,0,1] row_mask:0xf bank_mask:0xf
	v_max_u32_dpp v173, v170, v170 quad_perm:[2,3,0,1] row_mask:0xf bank_mask:0xf
	v_min_u32_dpp v175, v171, v171 quad_perm:[2,3,0,1] row_mask:0xf bank_mask:0xf
	v_max_u32_dpp v176, v171, v171 quad_perm:[2,3,0,1] row_mask:0xf bank_mask:0xf
	v_cndmask_b32_e64 v170, v173, v172, s[62:63]
	v_cndmask_b32_e64 v171, v176, v175, s[62:63]
	s_xnor_b64 s[62:63], s[50:51], s[60:61]
	s_nop 1
	v_min_u32_dpp v172, v170, v170 quad_perm:[1,0,3,2] row_mask:0xf bank_mask:0xf
	v_max_u32_dpp v173, v170, v170 quad_perm:[1,0,3,2] row_mask:0xf bank_mask:0xf
	v_min_u32_dpp v175, v171, v171 quad_perm:[1,0,3,2] row_mask:0xf bank_mask:0xf
	v_max_u32_dpp v176, v171, v171 quad_perm:[1,0,3,2] row_mask:0xf bank_mask:0xf
	v_cndmask_b32_e64 v170, v173, v172, s[62:63]
	v_cndmask_b32_e64 v171, v176, v175, s[62:63]
	ds_bpermute_b32 v174, v129, v170
	ds_bpermute_b32 v177, v129, v171
	s_waitcnt lgkmcnt(1)
	v_min_u32_e32 v172, v174, v170
	v_max_u32_e32 v173, v174, v170
	s_waitcnt lgkmcnt(0)
	v_min_u32_e32 v175, v177, v171
	v_max_u32_e32 v176, v177, v171
	v_cndmask_b32_e64 v170, v173, v172, s[60:61]
	v_cndmask_b32_e64 v171, v175, v176, s[60:61]
	ds_bpermute_b32 v174, v146, v170
	ds_bpermute_b32 v177, v146, v171
	s_waitcnt lgkmcnt(1)
	v_min_u32_e32 v172, v174, v170
	v_max_u32_e32 v173, v174, v170
	s_waitcnt lgkmcnt(0)
	v_min_u32_e32 v175, v177, v171
	v_max_u32_e32 v176, v177, v171
	v_cndmask_b32_e64 v170, v173, v172, s[58:59]
	v_cndmask_b32_e64 v171, v175, v176, s[58:59]
	s_nop 1
	v_min_u32_dpp v172, v170, v170 row_ror:8 row_mask:0xf bank_mask:0xf
	v_max_u32_dpp v173, v170, v170 row_ror:8 row_mask:0xf bank_mask:0xf
	v_min_u32_dpp v175, v171, v171 row_ror:8 row_mask:0xf bank_mask:0xf
	v_max_u32_dpp v176, v171, v171 row_ror:8 row_mask:0xf bank_mask:0xf
	v_cndmask_b32_e64 v170, v173, v172, s[56:57]
	v_cndmask_b32_e64 v171, v175, v176, s[56:57]
	s_nop 1
	v_mov_b32_dpp v174, v170 row_half_mirror row_mask:0xf bank_mask:0xf
	v_mov_b32_dpp v177, v171 row_half_mirror row_mask:0xf bank_mask:0xf
	s_nop 0
	v_min_u32_dpp v172, v174, v170 quad_perm:[3,2,1,0] row_mask:0xf bank_mask:0xf
	v_max_u32_dpp v173, v174, v170 quad_perm:[3,2,1,0] row_mask:0xf bank_mask:0xf
	v_min_u32_dpp v175, v177, v171 quad_perm:[3,2,1,0] row_mask:0xf bank_mask:0xf
	v_max_u32_dpp v176, v177, v171 quad_perm:[3,2,1,0] row_mask:0xf bank_mask:0xf
	v_cndmask_b32_e64 v170, v173, v172, s[54:55]
	v_cndmask_b32_e64 v171, v175, v176, s[54:55]
	s_nop 1
	v_min_u32_dpp v172, v170, v170 quad_perm:[2,3,0,1] row_mask:0xf bank_mask:0xf
	v_max_u32_dpp v173, v170, v170 quad_perm:[2,3,0,1] row_mask:0xf bank_mask:0xf
	v_min_u32_dpp v175, v171, v171 quad_perm:[2,3,0,1] row_mask:0xf bank_mask:0xf
	v_max_u32_dpp v176, v171, v171 quad_perm:[2,3,0,1] row_mask:0xf bank_mask:0xf
	v_cndmask_b32_e64 v170, v173, v172, s[52:53]
	v_cndmask_b32_e64 v171, v175, v176, s[52:53]
	s_nop 1
	v_min_u32_dpp v172, v170, v170 quad_perm:[1,0,3,2] row_mask:0xf bank_mask:0xf
	v_max_u32_dpp v173, v170, v170 quad_perm:[1,0,3,2] row_mask:0xf bank_mask:0xf
	v_min_u32_dpp v175, v171, v171 quad_perm:[1,0,3,2] row_mask:0xf bank_mask:0xf
	v_max_u32_dpp v176, v171, v171 quad_perm:[1,0,3,2] row_mask:0xf bank_mask:0xf
	v_cndmask_b32_e64 v170, v173, v172, s[50:51]
	v_cndmask_b32_e64 v171, v175, v176, s[50:51]
	v_min_u32_e32 v172, v170, v171
	v_max_u32_e32 v171, v170, v171
	v_mov_b32_e32 v170, v172
	ds_bpermute_b32 v174, v129, v170
	ds_bpermute_b32 v177, v129, v171
	s_waitcnt lgkmcnt(1)
	v_min_u32_e32 v172, v174, v170
	v_max_u32_e32 v173, v174, v170
	s_waitcnt lgkmcnt(0)
	v_min_u32_e32 v175, v177, v171
	v_max_u32_e32 v176, v177, v171
	v_cndmask_b32_e64 v170, v173, v172, s[60:61]
	v_cndmask_b32_e64 v171, v176, v175, s[60:61]
	ds_bpermute_b32 v174, v146, v170
	ds_bpermute_b32 v177, v146, v171
	s_waitcnt lgkmcnt(1)
	v_min_u32_e32 v172, v174, v170
	v_max_u32_e32 v173, v174, v170
	s_waitcnt lgkmcnt(0)
; __device__ __forceinline__ float bf_lo(unsigned u) { return __uint_as_float(u << 16); }
; __device__ __forceinline__ float bf_hi(unsigned u) { return __uint_as_float(u & 0xffff0000u); }
; #define PU_LOAD(BUF, EV, S0) do { _Pragma("unroll") for (int i = 0; i < 8; ++i) { const int row_ = __builtin_amdgcn_readlane(EV, (S0) + i); BUF[i & 3][i >> 2] = *(const u32x4*)(PU8 + (size_t)row_ * 1024 + lane * 16); } } while (0)
; __global__ void __launch_bounds__(NT, 2) mk_fwd(Args args) {
;     ...
;             for (int j = 0; j < 4; ++j) { const u32x4 a = *(const u32x4*)(HB + (size_t)tok * DM + lane * 32 + j * 8);
; #pragma unroll
;                 for (int q = 0; q < 4; ++q) hf2[j * 4 + q] = (f32x2){bf_lo(a[q]), bf_hi(a[q])}; }
;             const int e0 = EIDX[(size_t)tok * 128 + lane], e1 = EIDX[(size_t)tok * 128 + 64 + lane];
;             const float g0 = GATE[(size_t)tok * 128 + lane], g1 = GATE[(size_t)tok * 128 + 64 + lane];
;             const bool hi32 = (lane & 32) != 0, hi16 = (lane & 16) != 0; const int l3 = (lane & 3) << 4;
;     ...
;             float act0 = 0.f, act1 = 0.f;
;             u32x4 bA[4][2], bB[4][2];
; #pragma unroll
;             for (int hh = 0; hh < 2; ++hh) {
;                 const int ev = hh ? e1 : e0; const float gv = hh ? g1 : g0; float dv = 0.f;
;                 PU_LOAD(bA, ev, 0);
	v_min_u32_e32 v175, v177, v171
	v_max_u32_e32 v176, v177, v171
	v_cndmask_b32_e64 v170, v173, v172, s[58:59]
	v_cndmask_b32_e64 v171, v176, v175, s[58:59]
	s_nop 1
	v_min_u32_dpp v172, v170, v170 row_ror:8 row_mask:0xf bank_mask:0xf
	v_max_u32_dpp v173, v170, v170 row_ror:8 row_mask:0xf bank_mask:0xf
	v_min_u32_dpp v175, v171, v171 row_ror:8 row_mask:0xf bank_mask:0xf
	v_max_u32_dpp v176, v171, v171 row_ror:8 row_mask:0xf bank_mask:0xf
	v_cndmask_b32_e64 v170, v173, v172, s[56:57]
	v_cndmask_b32_e64 v171, v176, v175, s[56:57]
	s_nop 1
	v_mov_b32_dpp v174, v170 row_half_mirror row_mask:0xf bank_mask:0xf
	v_mov_b32_dpp v177, v171 row_half_mirror row_mask:0xf bank_mask:0xf
	s_nop 0
	v_min_u32_dpp v172, v174, v170 quad_perm:[3,2,1,0] row_mask:0xf bank_mask:0xf
	v_max_u32_dpp v173, v174, v170 quad_perm:[3,2,1,0] row_mask:0xf bank_mask:0xf
	v_min_u32_dpp v175, v177, v171 quad_perm:[3,2,1,0] row_mask:0xf bank_mask:0xf
	v_max_u32_dpp v176, v177, v171 quad_perm:[3,2,1,0] row_mask:0xf bank_mask:0xf
	v_cndmask_b32_e64 v170, v173, v172, s[54:55]
	v_cndmask_b32_e64 v171, v176, v175, s[54:55]
	s_nop 1
	v_min_u32_dpp v172, v170, v170 quad_perm:[2,3,0,1] row_mask:0xf bank_mask:0xf
	v_max_u32_dpp v173, v170, v170 quad_perm:[2,3,0,1] row_mask:0xf bank_mask:0xf
	v_min_u32_dpp v175, v171, v171 quad_perm:[2,3,0,1] row_mask:0xf bank_mask:0xf
	v_max_u32_dpp v176, v171, v171 quad_perm:[2,3,0,1] row_mask:0xf bank_mask:0xf
	v_cndmask_b32_e64 v170, v173, v172, s[52:53]
	v_cndmask_b32_e64 v171, v176, v175, s[52:53]
	s_nop 1
	v_min_u32_dpp v172, v170, v170 quad_perm:[1,0,3,2] row_mask:0xf bank_mask:0xf
	v_max_u32_dpp v173, v170, v170 quad_perm:[1,0,3,2] row_mask:0xf bank_mask:0xf
	v_min_u32_dpp v175, v171, v171 quad_perm:[1,0,3,2] row_mask:0xf bank_mask:0xf
	v_max_u32_dpp v176, v171, v171 quad_perm:[1,0,3,2] row_mask:0xf bank_mask:0xf
	v_cndmask_b32_e64 v170, v173, v172, s[50:51]
	v_cndmask_b32_e64 v171, v176, v175, s[50:51]
	v_and_b32_e32 v172, 63, v170
	v_lshlrev_b32_e32 v172, 2, v172
	ds_bpermute_b32 v173, v172, v110
	ds_bpermute_b32 v174, v172, v156
	v_and_b32_e32 v175, 63, v171
	v_lshlrev_b32_e32 v175, 2, v175
	ds_bpermute_b32 v176, v175, v110
	ds_bpermute_b32 v177, v175, v156
	v_and_b32_e32 v172, 64, v170
	v_cmp_eq_u32_e32 vcc, 0, v172
	s_waitcnt lgkmcnt(2)
	v_lshrrev_b32_e32 v108, 7, v170
	v_cndmask_b32_e32 v178, v174, v173, vcc
	v_and_b32_e32 v175, 64, v171
	v_cmp_eq_u32_e32 vcc, 0, v175
	s_waitcnt lgkmcnt(0)
	v_lshrrev_b32_e32 v106, 7, v171
	v_cndmask_b32_e32 v179, v177, v176, vcc
	v_mov_b32_e32 v110, v178
	v_mov_b32_e32 v156, v179
	s_mov_b32 s10, 0
	v_mov_b32_e32 v107, 0
	s_waitcnt vmcnt(6)
	v_lshlrev_b32_e32 v88, 16, v32
	v_readlane_b32 s4, v108, 0
	v_readlane_b32 s30, v108, 1
	v_readlane_b32 s34, v108, 2
	v_readlane_b32 s36, v108, 3
	v_readlane_b32 s38, v108, 4
	v_readlane_b32 s40, v108, 5
	v_readlane_b32 s42, v108, 6
	v_readlane_b32 s44, v108, 7
	s_ashr_i32 s5, s4, 31
	s_ashr_i32 s31, s30, 31
	s_ashr_i32 s35, s34, 31
	s_ashr_i32 s37, s36, 31
	s_ashr_i32 s39, s38, 31
	s_ashr_i32 s41, s40, 31
	s_ashr_i32 s43, s42, 31
	s_ashr_i32 s45, s44, 31
	s_lshl_b64 s[4:5], s[4:5], 10
	s_lshl_b64 s[30:31], s[30:31], 10
	s_lshl_b64 s[34:35], s[34:35], 10
	s_lshl_b64 s[36:37], s[36:37], 10
	s_lshl_b64 s[38:39], s[38:39], 10
	s_lshl_b64 s[40:41], s[40:41], 10
	s_lshl_b64 s[42:43], s[42:43], 10
	s_lshl_b64 s[44:45], s[44:45], 10
	v_lshl_add_u64 v[48:49], v[98:99], 0, s[4:5]
	v_lshl_add_u64 v[50:51], v[98:99], 0, s[30:31]
	v_lshl_add_u64 v[52:53], v[98:99], 0, s[34:35]
	v_lshl_add_u64 v[54:55], v[98:99], 0, s[36:37]
	v_lshl_add_u64 v[56:57], v[98:99], 0, s[38:39]
	v_lshl_add_u64 v[58:59], v[98:99], 0, s[40:41]
	v_lshl_add_u64 v[60:61], v[98:99], 0, s[42:43]
	v_lshl_add_u64 v[62:63], v[98:99], 0, s[44:45]
	global_load_dwordx4 v[0:3], v[48:49], off
	global_load_dwordx4 v[4:7], v[50:51], off
	global_load_dwordx4 v[8:11], v[52:53], off
	global_load_dwordx4 v[12:15], v[54:55], off
	global_load_dwordx4 v[16:19], v[56:57], off
	global_load_dwordx4 v[20:23], v[58:59], off
	global_load_dwordx4 v[24:27], v[60:61], off
	global_load_dwordx4 v[28:31], v[62:63], off
	s_waitcnt vmcnt(11)
	v_lshlrev_b32_e32 v64, 16, v44
	v_and_b32_e32 v65, 0xffff0000, v44
	v_lshlrev_b32_e32 v66, 16, v45
	v_and_b32_e32 v67, 0xffff0000, v45
	v_lshlrev_b32_e32 v68, 16, v46
	v_and_b32_e32 v69, 0xffff0000, v46
	v_lshlrev_b32_e32 v70, 16, v47
	v_and_b32_e32 v71, 0xffff0000, v47
	v_lshlrev_b32_e32 v72, 16, v40
	v_and_b32_e32 v73, 0xffff0000, v40
	v_lshlrev_b32_e32 v74, 16, v41
	v_and_b32_e32 v75, 0xffff0000, v41
	v_lshlrev_b32_e32 v76, 16, v42
	v_and_b32_e32 v77, 0xffff0000, v42
	v_lshlrev_b32_e32 v78, 16, v43
	v_and_b32_e32 v79, 0xffff0000, v43
	v_lshlrev_b32_e32 v80, 16, v36
	v_and_b32_e32 v81, 0xffff0000, v36
	v_lshlrev_b32_e32 v82, 16, v37
	v_and_b32_e32 v83, 0xffff0000, v37
	v_lshlrev_b32_e32 v84, 16, v38
	v_and_b32_e32 v85, 0xffff0000, v38
	v_lshlrev_b32_e32 v86, 16, v39
	v_and_b32_e32 v87, 0xffff0000, v39
	v_and_b32_e32 v89, 0xffff0000, v32
	v_lshlrev_b32_e32 v90, 16, v33
	v_and_b32_e32 v91, 0xffff0000, v33
	v_lshlrev_b32_e32 v92, 16, v34
	v_and_b32_e32 v93, 0xffff0000, v34
	v_lshlrev_b32_e32 v94, 16, v35
	v_and_b32_e32 v95, 0xffff0000, v35
